# compressed-branch loops: K blocks loaded once per workgroup into a 3-slot LDS ring by LDS-DMA (static LDS +28 KB), one barrier per block
# baseline (speedup 1.0000x reference)
; #define LAS __attribute__((address_space(3)))
; template <int MODE>
; __device__ __forceinline__ void softmax_block(f32x4 (&acc)[4], int base, bool ok, int t, int g4, const LAS float* lutg, SmState& st, f32x4 (&O)[4], bf16x8 (&pB)[2]) {
;     float mx = -1e30f; unsigned vm = 0u;
; #pragma unroll
;     for (int nt = 0; nt < 4; ++nt)
; #pragma unroll
;         for (int i = 0; i < 4; ++i) {
;             const int key = base + 16 * nt + 4 * g4 + i;
;             const int dist = (MODE == 0) ? t - (16 * key + 31) : t - key;
;             bool valid = dist >= 0;
;             if (MODE == 1) valid = valid && ok;
;             if (MODE == 2) valid = valid && dist < 512;
;             int dc = dist < 0 ? 0 : dist; dc = dc > 1023 ? 1023 : dc;
;             const float lg = acc[nt][i] + lutg[dc * 4];
;             acc[nt][i] = lg;
;             if (valid) { mx = fmaxf(mx, lg); vm |= 1u << (nt * 4 + i); }
; __device__ __forceinline__ void nsa_wave(CArgs* Ap, int l, int b, int g, int tq0, const LAS float* lut, LAS float* imp, int lane) {
;     ...
;         for (int cb = 0; cb < ncb; ++cb) {
;             bf16x8 kf[4][2]; load_k(kf, KC + (size_t)cb * 4096, lane);
;             f32x4 acc[4];
; #pragma unroll
;             for (int nt = 0; nt < 4; ++nt) acc[nt] = (f32x4){0.f, 0.f, 0.f, 0.f};
;             qk_acc(acc, kf, qB);
;             softmax_block<0>(acc, cb * 64, true, t, g4, lutg, st, Od, pB);
.LBB0_895:
	s_lshl_b32 s20, s0, 2
	s_sub_i32 s0, s19, 28
	s_lshr_b32 s21, s0, 10
	v_lshl_add_u32 v206, s17, 14, v132
	s_andn2_b64 vcc, exec, s[46:47]
	v_add_u32_e32 v75, s18, v202
	s_cbranch_vccnz .LBB0_899
	s_and_b32 s27, s19, 0x3e0
	s_cmp_eq_u32 s27, 0
	s_cbranch_scc1 .Lc1_orig
	s_add_i32 s0, s20, s17
	s_ashr_i32 s1, s0, 31
	s_add_i32 s72, s21, 1
	s_lshl_b64 s[0:1], s[0:1], 16
	s_add_u32 s0, s15, s0
	s_addc_u32 s1, s16, s1
	v_xor_b32_e32 v21, 16, v170
	v_xor_b32_e32 v22, 32, v170
	v_lshl_add_u64 v[102:103], s[0:1], 0, v[84:85]
	s_mov_b32 s23, 0x2a201000
	v_add_co_u32_e32 v100, vcc, s23, v102
	v_add_u32_e32 v122, s18, v202
	s_mov_b64 s[0:1], 0x2000
	v_addc_co_u32_e32 v101, vcc, 0, v103, vcc
	v_mov_b32_e32 v76, 0xf149f2ca
	v_mov_b32_e32 v8, 0
	s_sub_i32 s27, s93, 0x10000
	s_lshr_b32 s27, s27, 13
	s_lshl_b32 s28, s27, 10
	s_sub_i32 s30, s28, 0x1000
	s_ashr_i32 s31, s30, 31
	v_lshl_add_u64 v[102:103], v[100:101], 0, s[30:31]
	s_add_i32 s29, s28, 0x21000
	v_lshlrev_b32_e32 v119, 4, v89
	v_add_u32_e32 v119, 0x21000, v119
	s_waitcnt lgkmcnt(0)
	s_barrier
	s_mov_b32 m0, s29
	s_nop 0
	global_load_lds_dwordx4 v[102:103], off
	s_cmp_gt_u32 s72, 1
	s_cbranch_scc0 .Lc1s_hold1
	v_lshl_add_u64 v[102:103], v[102:103], 0, s[0:1]
.Lc1s_hold1:
	s_add_i32 m0, s29, 0x2000
	s_nop 0
	global_load_lds_dwordx4 v[102:103], off
	s_movk_i32 s34, 0x4000
	s_mov_b32 s35, 0
	ds_read_b32 v125, v206 offset:16368
.Lc1s_loop:
	s_waitcnt vmcnt(1)
	s_barrier
	s_cmp_gt_u32 s72, 2
	s_cbranch_scc0 .Lc1s_hold
	v_lshl_add_u64 v[102:103], v[102:103], 0, s[0:1]
.Lc1s_hold:
	s_add_i32 m0, s29, s34
	s_nop 0
	global_load_lds_dwordx4 v[102:103], off
	s_add_i32 s34, s34, 0x2000
	s_cmp_eq_u32 s34, 0x6000
	s_cselect_b32 s34, 0, s34
	v_add_u32_e32 v133, s35, v119
	ds_read_b128 v[24:27], v133
	ds_read_b128 v[28:31], v133 offset:1024
	ds_read_b128 v[32:35], v133 offset:2048
	ds_read_b128 v[36:39], v133 offset:3072
	ds_read_b128 v[40:43], v133 offset:4096
	ds_read_b128 v[44:47], v133 offset:5120
	ds_read_b128 v[48:51], v133 offset:6144
	ds_read_b128 v[52:55], v133 offset:7168
	s_add_i32 s35, s35, 0x2000
	s_cmp_eq_u32 s35, 0x6000
	s_cselect_b32 s35, 0, s35
	v_cmp_lt_i32_e32 vcc, 0x3fe, v122
	s_cmp_eq_u64 vcc, exec
	s_cselect_b32 s26, 1, 0
	s_cbranch_scc1 .Lc1s_lutskip
	v_add_u32_e32 v244, 0x330, v122
	v_cmp_lt_i32_e64 s[46:47], -1, v244
	v_med3_i32 v244, v244, 0, v181
	v_lshl_add_u32 v244, v244, 4, v206
	ds_read_b32 v244, v244
	v_add_u32_e32 v245, 0x320, v122
	v_cmp_lt_i32_e64 s[48:49], -1, v245
	v_med3_i32 v245, v245, 0, v181
	v_lshl_add_u32 v245, v245, 4, v206
	ds_read_b32 v245, v245
	v_add_u32_e32 v246, 0x310, v122
	v_cmp_lt_i32_e64 s[50:51], -1, v246
	v_med3_i32 v246, v246, 0, v181
	v_lshl_add_u32 v246, v246, 4, v206
	ds_read_b32 v246, v246
	v_add_u32_e32 v247, 0x300, v122
	v_cmp_lt_i32_e64 s[52:53], -1, v247
	v_med3_i32 v247, v247, 0, v181
	v_lshl_add_u32 v247, v247, 4, v206
	ds_read_b32 v247, v247
	v_add_u32_e32 v248, 0x230, v122
	v_cmp_lt_i32_e64 s[54:55], -1, v248
	v_med3_i32 v248, v248, 0, v181
	v_lshl_add_u32 v248, v248, 4, v206
	ds_read_b32 v248, v248
	v_add_u32_e32 v249, 0x220, v122
	v_cmp_lt_i32_e64 s[56:57], -1, v249
	v_med3_i32 v249, v249, 0, v181
	v_lshl_add_u32 v249, v249, 4, v206
	ds_read_b32 v249, v249
	v_add_u32_e32 v250, 0x210, v122
	v_cmp_lt_i32_e64 s[58:59], -1, v250
	v_med3_i32 v250, v250, 0, v181
	v_lshl_add_u32 v250, v250, 4, v206
	ds_read_b32 v250, v250
	v_add_u32_e32 v251, 0x200, v122
	v_cmp_lt_i32_e64 s[60:61], -1, v251
	v_med3_i32 v251, v251, 0, v181
	v_lshl_add_u32 v251, v251, 4, v206
	ds_read_b32 v251, v251
	v_add_u32_e32 v252, 0x130, v122
	v_cmp_lt_i32_e64 s[62:63], -1, v252
	v_med3_i32 v252, v252, 0, v181
	v_lshl_add_u32 v252, v252, 4, v206
	ds_read_b32 v252, v252
	v_add_u32_e32 v253, 0x120, v122
	v_cmp_lt_i32_e64 s[64:65], -1, v253
	v_med3_i32 v253, v253, 0, v181
	v_lshl_add_u32 v253, v253, 4, v206
	ds_read_b32 v253, v253
	v_add_u32_e32 v255, 0x110, v122
	v_cmp_lt_i32_e64 s[66:67], -1, v255
	v_med3_i32 v255, v255, 0, v181
	v_lshl_add_u32 v255, v255, 4, v206
	ds_read_b32 v255, v255
	v_add_u32_e32 v98, 0x100, v122
	v_cmp_lt_i32_e64 s[68:69], -1, v98
	v_med3_i32 v98, v98, 0, v181
	v_lshl_add_u32 v98, v98, 4, v206
	ds_read_b32 v98, v98
	v_add_u32_e32 v99, 0x30, v122
	v_cmp_lt_i32_e64 s[24:25], -1, v99
	v_med3_i32 v99, v99, 0, v181
	v_lshl_add_u32 v99, v99, 4, v206
	ds_read_b32 v99, v99
	v_add_u32_e32 v116, 0x20, v122
	v_cmp_lt_i32_e64 s[98:99], -1, v116
	v_med3_i32 v116, v116, 0, v181
	v_lshl_add_u32 v116, v116, 4, v206
	ds_read_b32 v116, v116
	v_add_u32_e32 v117, 0x10, v122
	v_cmp_lt_i32_e64 s[100:101], -1, v117
	v_med3_i32 v117, v117, 0, v181
	v_lshl_add_u32 v117, v117, 4, v206
	ds_read_b32 v117, v117
	v_add_u32_e32 v118, 0x0, v122
	v_cmp_lt_i32_e64 s[22:23], -1, v118
	v_med3_i32 v118, v118, 0, v181
	v_lshl_add_u32 v118, v118, 4, v206
	ds_read_b32 v118, v118
.Lc1s_lutskip:
	v_add_u32_e32 v122, 0xfffffc00, v122
	s_add_i32 s72, s72, -1
	s_waitcnt lgkmcnt(0)
	v_mfma_f32_16x16x32_bf16 v[228:231], v[24:27], v[0:3], 0
	v_mfma_f32_16x16x32_bf16 v[232:235], v[32:35], v[0:3], 0
	v_mfma_f32_16x16x32_bf16 v[236:239], v[40:43], v[0:3], 0
	v_mfma_f32_16x16x32_bf16 v[240:243], v[48:51], v[0:3], 0
	v_mfma_f32_16x16x32_bf16 v[228:231], v[28:31], v[4:7], v[228:231]
	v_mfma_f32_16x16x32_bf16 v[232:235], v[36:39], v[4:7], v[232:235]
	v_mfma_f32_16x16x32_bf16 v[236:239], v[44:47], v[4:7], v[236:239]
	v_mfma_f32_16x16x32_bf16 v[240:243], v[52:55], v[4:7], v[240:243]

; __device__ __forceinline__ float fexp(float x) { return __expf(x); }
; template <int MODE>
; __device__ __forceinline__ void softmax_block(f32x4 (&acc)[4], int base, bool ok, int t, int g4, const LAS float* lutg, SmState& st, f32x4 (&O)[4], bf16x8 (&pB)[2]) {
;     ...
;     const float mn = fmaxf(st.m, mx);
;     const float sc = fexp(st.m - mn);
;     float ls = 0.f;
; #pragma unroll
;     for (int nt = 0; nt < 4; ++nt)
; #pragma unroll
;         for (int i = 0; i < 4; ++i) { const float p = ((vm >> (nt * 4 + i)) & 1u) ? fexp(acc[nt][i] - mn) : 0.f; acc[nt][i] = p; ls += p; }
;     st.l = st.l * sc + ls; st.m = mn;
; __device__ __forceinline__ void nsa_wave(CArgs* Ap, int l, int b, int g, int tq0, const LAS float* lut, LAS float* imp, int lane) {
;     ...
;         for (int cb = 0; cb < ncb; ++cb) {
;             bf16x8 kf[4][2]; load_k(kf, KC + (size_t)cb * 4096, lane);
;             f32x4 acc[4];
; #pragma unroll
;             for (int nt = 0; nt < 4; ++nt) acc[nt] = (f32x4){0.f, 0.f, 0.f, 0.f};
;             qk_acc(acc, kf, qB);
;             softmax_block<0>(acc, cb * 64, true, t, g4, lutg, st, Od, pB);
;         }
;         float lt = st.l; lt += __shfl_xor(lt, 16); lt += __shfl_xor(lt, 32);
.Lc1s_join:
	v_add_f32_e32 v120, v229, v228
	v_add_f32_e32 v120, v230, v120
	v_add_f32_e32 v120, v231, v120
	v_add_f32_e32 v120, v232, v120
	v_add_f32_e32 v120, v233, v120
	v_add_f32_e32 v120, v234, v120
	v_add_f32_e32 v120, v235, v120
	v_add_f32_e32 v120, v236, v120
	v_add_f32_e32 v120, v237, v120
	v_add_f32_e32 v120, v238, v120
	v_add_f32_e32 v120, v239, v120
	v_add_f32_e32 v120, v240, v120
	v_add_f32_e32 v120, v241, v120
	v_add_f32_e32 v120, v242, v120
	v_add_f32_e32 v120, v243, v120
	v_fmac_f32_e32 v120, v8, v126
	s_cmp_eq_u32 s72, 0
	v_mov_b32_e32 v8, v120
	s_cbranch_scc0 .Lc1s_loop
	v_mov_b32_e32 v74, v170
	v_mov_b32_e32 v73, v177
	v_mov_b32_e32 v77, v171
	s_waitcnt vmcnt(0)
	s_branch .LBB0_900
.Lc1_orig:
	s_add_i32 s0, s20, s17
	s_ashr_i32 s1, s0, 31
	s_add_i32 s72, s21, 1
	s_lshl_b64 s[0:1], s[0:1], 16
	s_add_u32 s0, s15, s0
	s_addc_u32 s1, s16, s1
	v_xor_b32_e32 v21, 16, v170
	v_xor_b32_e32 v22, 32, v170
	v_lshl_add_u64 v[102:103], s[0:1], 0, v[84:85]
	s_mov_b32 s23, 0x2a201000
	v_add_co_u32_e32 v100, vcc, s23, v102
	v_add_u32_e32 v122, s18, v202
	s_mov_b64 s[0:1], 0x2000
	v_addc_co_u32_e32 v101, vcc, 0, v103, vcc
	v_mov_b32_e32 v76, 0xf149f2ca
	v_mov_b32_e32 v8, 0
	global_load_dwordx4 v[24:27], v[100:101], off offset:-4096
	global_load_dwordx4 v[28:31], v[100:101], off offset:-3072
	global_load_dwordx4 v[32:35], v[100:101], off offset:-2048
	global_load_dwordx4 v[36:39], v[100:101], off offset:-1024
	global_load_dwordx4 v[40:43], v[100:101], off offset:0
	global_load_dwordx4 v[44:47], v[100:101], off offset:1024
	global_load_dwordx4 v[48:51], v[100:101], off offset:2048
	global_load_dwordx4 v[52:55], v[100:101], off offset:3072
	ds_read_b32 v125, v206 offset:16368

; __device__ __forceinline__ void nsa_wave(CArgs* Ap, int l, int b, int g, int tq0, const LAS float* lut, LAS float* imp, int lane) {
;     ...
;         float lt = st.l; lt += __shfl_xor(lt, 16); lt += __shfl_xor(lt, 32);
;         const float inv = 1.f / fmaxf(lt, 1e-30f), mfin = st.m;
;         for (int cb = 0; cb < ncb; ++cb) {
;             bf16x8 kf[4][2]; load_k(kf, KC + (size_t)cb * 4096, lane);
;             bf16x8 vf[4][2]; load_v(vf, VCT + (size_t)cb * 4096, lane);
;             f32x4 acc[4];
; #pragma unroll
;             for (int nt = 0; nt < 4; ++nt) acc[nt] = (f32x4){0.f, 0.f, 0.f, 0.f};
;             qk_acc(acc, kf, qB);
.LBB0_900:
	v_lshlrev_b32_e32 v207, 6, v20
	v_cmp_lt_i32_e32 vcc, v21, v77
	v_mov_b32_e32 v19, 0
	v_xor_b32_e32 v79, 1, v74
	v_cndmask_b32_e32 v9, v74, v21, vcc
	v_lshlrev_b32_e32 v209, 2, v9
	ds_bpermute_b32 v9, v209, v8
	v_cmp_lt_i32_e32 vcc, v22, v77
	v_xor_b32_e32 v78, 2, v74
	v_cmp_lt_i32_e64 s[48:49], v79, v77
	v_cndmask_b32_e32 v10, v74, v22, vcc
	v_lshlrev_b32_e32 v208, 2, v10
	s_waitcnt lgkmcnt(0)
	v_add_f32_e32 v24, v8, v9
	ds_bpermute_b32 v25, v208, v24
	s_andn2_b64 vcc, exec, s[96:97]
	v_cmp_lt_i32_e64 s[46:47], v78, v77
	v_mov_b32_e32 v18, v19
	v_mov_b32_e32 v17, v19
	v_mov_b32_e32 v16, v19
	v_mov_b32_e32 v11, v19
	v_mov_b32_e32 v10, v19
	v_mov_b32_e32 v9, v19
	v_mov_b32_e32 v8, v19
	v_mov_b32_e32 v15, v19
	v_mov_b32_e32 v14, v19
	v_mov_b32_e32 v13, v19
	v_mov_b32_e32 v12, v19
	v_mov_b32_e32 v23, v19
	v_mov_b32_e32 v22, v19
	v_mov_b32_e32 v21, v19
	v_mov_b32_e32 v20, v19
	s_cbranch_vccnz .LBB0_943
	s_and_b32 s27, s19, 0x3e0
	s_cmp_eq_u32 s27, 0
	s_cbranch_scc1 .Lc2_orig
	s_waitcnt lgkmcnt(0)
	v_add_f32_e32 v8, v24, v25
	v_max_f32_e32 v8, 0xda24260, v8
	v_div_scale_f32 v9, s[0:1], v8, v8, 1.0
	v_rcp_f32_e32 v10, v9
	v_div_scale_f32 v11, vcc, 1.0, v8, 1.0
	s_add_i32 s0, s20, s17
	v_fma_f32 v12, -v9, v10, 1.0
	v_fmac_f32_e32 v10, v12, v10
	v_mul_f32_e32 v12, v11, v10
	v_fma_f32 v13, -v9, v12, v11
	v_fmac_f32_e32 v12, v13, v10
	v_fma_f32 v9, -v9, v12, v11
	v_div_fmas_f32 v9, v9, v10, v12
	v_div_fixup_f32 v80, v9, v8, 1.0
	s_lshl_b32 s21, s21, 8
	s_ashr_i32 s1, s0, 31
	s_addk_i32 s21, 0x100
	s_lshl_b64 s[0:1], s[0:1], 16
	s_add_u32 s0, s15, s0
	s_addc_u32 s1, s16, s1
	s_mov_b32 s22, 0
	v_mov_b32_e32 v8, 0
	v_mov_b32_e32 v9, 0
	v_mov_b32_e32 v10, 0
	v_mov_b32_e32 v11, 0
	v_mov_b32_e32 v12, 0
	v_mov_b32_e32 v13, 0
	v_mov_b32_e32 v14, 0
	v_mov_b32_e32 v15, 0
	v_mov_b32_e32 v16, 0
	v_mov_b32_e32 v17, 0
	v_mov_b32_e32 v18, 0
	v_mov_b32_e32 v19, 0
	v_mov_b32_e32 v20, 0
	v_mov_b32_e32 v21, 0
	v_mov_b32_e32 v22, 0
	v_mov_b32_e32 v23, 0
	v_lshl_add_u64 v[126:127], s[0:1], 0, v[84:85]
	s_mov_b32 s23, 0x2a201000
	v_add_co_u32_e32 v120, vcc, s23, v126
	s_mov_b32 s23, 0x2a601000
	s_nop 0
	v_addc_co_u32_e32 v121, vcc, 0, v127, vcc
	v_add_co_u32_e32 v122, vcc, s23, v126
	v_add_u32_e32 v124, 0x10000, v203
	s_mov_b64 s[0:1], 0x2000
	v_addc_co_u32_e32 v123, vcc, 0, v127, vcc
	s_sub_i32 s27, s93, 0x10000
	s_lshr_b32 s27, s27, 13
	s_lshl_b32 s28, s27, 10
	s_sub_i32 s30, s28, 0x1000
	s_ashr_i32 s31, s30, 31
	v_lshl_add_u64 v[134:135], v[120:121], 0, s[30:31]
	s_add_i32 s29, s28, 0x21000
	v_lshlrev_b32_e32 v119, 4, v89
	v_add_u32_e32 v119, 0x21000, v119
	s_waitcnt lgkmcnt(0)
	s_barrier
	s_mov_b32 m0, s29
	s_nop 0
	global_load_lds_dwordx4 v[134:135], off
	s_cmp_gt_u32 s21, 0x100
	s_cbranch_scc0 .Lc2s_hold1
	v_lshl_add_u64 v[134:135], v[134:135], 0, s[0:1]
.Lc2s_hold1:
	s_add_i32 m0, s29, 0x2000
	s_nop 0
	global_load_lds_dwordx4 v[134:135], off
	s_movk_i32 s34, 0x4000
	s_mov_b32 s35, 0
	global_load_dwordx4 v[56:59], v[122:123], off offset:-4096
	global_load_dwordx4 v[60:63], v[122:123], off offset:-3072
	global_load_dwordx4 v[64:67], v[122:123], off offset:-2048
	global_load_dwordx4 v[68:71], v[122:123], off offset:-1024
	global_load_dwordx4 v[100:103], v[122:123], off offset:0
	global_load_dwordx4 v[104:107], v[122:123], off offset:1024
	global_load_dwordx4 v[108:111], v[122:123], off offset:2048
	global_load_dwordx4 v[112:115], v[122:123], off offset:3072
	v_mul_f32_e32 v126, 0xbfb8aa3b, v76
.Lc2s_loop:
	s_waitcnt vmcnt(9)
	s_barrier
	s_add_i32 s36, s22, 0x200
	s_cmp_lt_u32 s36, s21
	s_cbranch_scc0 .Lc2s_hold
	v_lshl_add_u64 v[134:135], v[134:135], 0, s[0:1]
; __device__ __forceinline__ void nsa_wave(CArgs* Ap, int l, int b, int g, int tq0, const LAS float* lut, LAS float* imp, int lane) {
;     ...
;         for (int cb = 0; cb < ncb; ++cb) {
;             bf16x8 kf[4][2]; load_k(kf, KC + (size_t)cb * 4096, lane);
;             bf16x8 vf[4][2]; load_v(vf, VCT + (size_t)cb * 4096, lane);
;             f32x4 acc[4];
; #pragma unroll
;             for (int nt = 0; nt < 4; ++nt) acc[nt] = (f32x4){0.f, 0.f, 0.f, 0.f};
;             qk_acc(acc, kf, qB);
; #pragma unroll
;             for (int nt = 0; nt < 4; ++nt) {
;                 f32x4 pi4;
; #pragma unroll
;                 for (int i = 0; i < 4; ++i) {
;                     const int key = cb * 64 + 16 * nt + 4 * g4 + i; const int dist = t - (16 * key + 31);
;                     int dc = dist < 0 ? 0 : dist; dc = dc > 1023 ? 1023 : dc;
;                     const float lg = acc[nt][i] + lutg[dc * 4];
.Lc2s_hold:
	s_add_i32 m0, s29, s34
	s_nop 0
	global_load_lds_dwordx4 v[134:135], off
	s_add_i32 s34, s34, 0x2000
	s_cmp_eq_u32 s34, 0x6000
	s_cselect_b32 s34, 0, s34
	v_add_u32_e32 v133, s35, v119
	ds_read_b128 v[24:27], v133
	ds_read_b128 v[28:31], v133 offset:1024
	ds_read_b128 v[32:35], v133 offset:2048
	ds_read_b128 v[36:39], v133 offset:3072
	ds_read_b128 v[40:43], v133 offset:4096
	ds_read_b128 v[44:47], v133 offset:5120
	ds_read_b128 v[48:51], v133 offset:6144
	ds_read_b128 v[52:55], v133 offset:7168
	s_add_i32 s35, s35, 0x2000
	s_cmp_eq_u32 s35, 0x6000
	s_cselect_b32 s35, 0, s35
	v_cmp_lt_i32_e32 vcc, 0x3fe, v75
	s_cmp_eq_u64 vcc, exec
	s_cselect_b32 s26, 1, 0
	s_cbranch_scc1 .Lc2s_lutskip
	v_add_u32_e32 v244, 0x330, v75
	v_cmp_lt_i32_e64 s[46:47], -1, v244
	v_min_u32_e32 v244, v181, v244
	v_lshl_add_u32 v244, v244, 4, v206
	ds_read_b32 v244, v244
	v_add_u32_e32 v245, 0x320, v75
	v_cmp_lt_i32_e64 s[48:49], -1, v245
	v_min_u32_e32 v245, v181, v245
	v_lshl_add_u32 v245, v245, 4, v206
	ds_read_b32 v245, v245
	v_add_u32_e32 v246, 0x310, v75
	v_cmp_lt_i32_e64 s[50:51], -1, v246
	v_min_u32_e32 v246, v181, v246
	v_lshl_add_u32 v246, v246, 4, v206
	ds_read_b32 v246, v246
	v_add_u32_e32 v247, 0x300, v75
	v_cmp_lt_i32_e64 s[52:53], -1, v247
	v_min_u32_e32 v247, v181, v247
	v_lshl_add_u32 v247, v247, 4, v206
	ds_read_b32 v247, v247
	v_add_u32_e32 v248, 0x230, v75
	v_cmp_lt_i32_e64 s[54:55], -1, v248
	v_min_u32_e32 v248, v181, v248
	v_lshl_add_u32 v248, v248, 4, v206
	ds_read_b32 v248, v248
	v_add_u32_e32 v249, 0x220, v75
	v_cmp_lt_i32_e64 s[56:57], -1, v249
	v_min_u32_e32 v249, v181, v249
	v_lshl_add_u32 v249, v249, 4, v206
	ds_read_b32 v249, v249
	v_add_u32_e32 v250, 0x210, v75
	v_cmp_lt_i32_e64 s[58:59], -1, v250
	v_min_u32_e32 v250, v181, v250
	v_lshl_add_u32 v250, v250, 4, v206
	ds_read_b32 v250, v250
	v_add_u32_e32 v251, 0x200, v75
	v_cmp_lt_i32_e64 s[60:61], -1, v251
	v_min_u32_e32 v251, v181, v251
	v_lshl_add_u32 v251, v251, 4, v206
	ds_read_b32 v251, v251
	v_add_u32_e32 v252, 0x130, v75
	v_cmp_lt_i32_e64 s[62:63], -1, v252
	v_min_u32_e32 v252, v181, v252
	v_lshl_add_u32 v252, v252, 4, v206
	ds_read_b32 v252, v252
	v_add_u32_e32 v253, 0x120, v75
	v_cmp_lt_i32_e64 s[64:65], -1, v253
	v_min_u32_e32 v253, v181, v253
	v_lshl_add_u32 v253, v253, 4, v206
	ds_read_b32 v253, v253
	v_add_u32_e32 v255, 0x110, v75
	v_cmp_lt_i32_e64 s[66:67], -1, v255
	v_min_u32_e32 v255, v181, v255
	v_lshl_add_u32 v255, v255, 4, v206
	ds_read_b32 v255, v255
	v_add_u32_e32 v98, 0x100, v75
	v_cmp_lt_i32_e64 s[68:69], -1, v98
	v_min_u32_e32 v98, v181, v98
	v_lshl_add_u32 v98, v98, 4, v206
	ds_read_b32 v98, v98
	v_add_u32_e32 v99, 0x30, v75
	v_cmp_lt_i32_e64 s[96:97], -1, v99
	v_min_u32_e32 v99, v181, v99
	v_lshl_add_u32 v99, v99, 4, v206
	ds_read_b32 v99, v99
	v_add_u32_e32 v116, 0x20, v75
	v_cmp_lt_i32_e64 s[98:99], -1, v116
	v_min_u32_e32 v116, v181, v116
	v_lshl_add_u32 v116, v116, 4, v206
	ds_read_b32 v116, v116
	v_add_u32_e32 v117, 0x10, v75
	v_cmp_lt_i32_e64 s[100:101], -1, v117
	v_min_u32_e32 v117, v181, v117
	v_lshl_add_u32 v117, v117, 4, v206
	ds_read_b32 v117, v117
	v_add_u32_e32 v118, 0x0, v75
	v_cmp_lt_i32_e64 s[76:77], -1, v118
	v_min_u32_e32 v118, v181, v118
	v_lshl_add_u32 v118, v118, 4, v206
	ds_read_b32 v118, v118
.Lc2s_lutskip:
	v_add_u32_e32 v75, 0xfffffc00, v75
	s_addk_i32 s22, 0x100
	s_waitcnt lgkmcnt(0)
	v_mfma_f32_16x16x32_bf16 v[228:231], v[24:27], v[0:3], 0
	v_mfma_f32_16x16x32_bf16 v[232:235], v[32:35], v[0:3], 0
	v_mfma_f32_16x16x32_bf16 v[236:239], v[40:43], v[0:3], 0
	v_mfma_f32_16x16x32_bf16 v[240:243], v[48:51], v[0:3], 0
	v_mfma_f32_16x16x32_bf16 v[228:231], v[28:31], v[4:7], v[228:231]
	v_mfma_f32_16x16x32_bf16 v[232:235], v[36:39], v[4:7], v[232:235]
	v_mfma_f32_16x16x32_bf16 v[236:239], v[44:47], v[4:7], v[236:239]
	v_mfma_f32_16x16x32_bf16 v[240:243], v[52:55], v[4:7], v[240:243]
	s_cmp_lg_u32 s22, s21
	s_cbranch_scc0 .Lc2s_nokpf
	v_lshl_add_u64 v[122:123], v[122:123], 0, s[0:1]

; #define LAS __attribute__((address_space(3)))
; __device__ __forceinline__ unsigned pk2(float lo, float hi) { return pg8::cvt_pk_bf16(lo, hi); }
; __device__ __forceinline__ float fexp(float x) { return __expf(x); }
; __device__ __forceinline__ void nsa_wave(CArgs* Ap, int l, int b, int g, int tq0, const LAS float* lut, LAS float* imp, int lane) {
;     ...
;                     float p = (dist >= 0) ? fexp(lg - mfin) * inv : 0.f;
;                     acc[nt][i] = p;
;                     p += __shfl_xor(p, 1); p += __shfl_xor(p, 2);
;                     pi4[i] = p;
;                 }
;                 if (r == 0) *(LAS f32x4*)(imp + qi * 512 + cb * 64 + 16 * nt + 4 * g4) = pi4;
;             }
; #pragma unroll
;             for (int hh = 0; hh < 2; ++hh) { u32x4 w; w.x = pk2(acc[2 * hh][0], acc[2 * hh][1]); w.y = pk2(acc[2 * hh][2], acc[2 * hh][3]); w.z = pk2(acc[2 * hh + 1][0], acc[2 * hh + 1][1]); w.w = pk2(acc[2 * hh + 1][2], acc[2 * hh + 1][3]);
;                 pB[hh] = __builtin_bit_cast(bf16x8, w); }
;             pv_acc(outacc, vf, pB);
.Lc2s_nomask:
	v_add_f32_dpp v228, v244, v244 quad_perm:[1,0,3,2] row_mask:0xf bank_mask:0xf
	v_add_f32_dpp v229, v245, v245 quad_perm:[1,0,3,2] row_mask:0xf bank_mask:0xf
	v_add_f32_dpp v230, v246, v246 quad_perm:[1,0,3,2] row_mask:0xf bank_mask:0xf
	v_add_f32_dpp v231, v247, v247 quad_perm:[1,0,3,2] row_mask:0xf bank_mask:0xf
	v_add_f32_dpp v232, v248, v248 quad_perm:[1,0,3,2] row_mask:0xf bank_mask:0xf
	v_add_f32_dpp v233, v249, v249 quad_perm:[1,0,3,2] row_mask:0xf bank_mask:0xf
	v_add_f32_dpp v234, v250, v250 quad_perm:[1,0,3,2] row_mask:0xf bank_mask:0xf
	v_add_f32_dpp v235, v251, v251 quad_perm:[1,0,3,2] row_mask:0xf bank_mask:0xf
	v_add_f32_dpp v236, v252, v252 quad_perm:[1,0,3,2] row_mask:0xf bank_mask:0xf
	v_add_f32_dpp v237, v253, v253 quad_perm:[1,0,3,2] row_mask:0xf bank_mask:0xf
	v_add_f32_dpp v238, v255, v255 quad_perm:[1,0,3,2] row_mask:0xf bank_mask:0xf
	v_add_f32_dpp v239, v98, v98 quad_perm:[1,0,3,2] row_mask:0xf bank_mask:0xf
	v_add_f32_dpp v240, v99, v99 quad_perm:[1,0,3,2] row_mask:0xf bank_mask:0xf
	v_add_f32_dpp v241, v116, v116 quad_perm:[1,0,3,2] row_mask:0xf bank_mask:0xf
	v_add_f32_dpp v242, v117, v117 quad_perm:[1,0,3,2] row_mask:0xf bank_mask:0xf
	v_add_f32_dpp v243, v118, v118 quad_perm:[1,0,3,2] row_mask:0xf bank_mask:0xf
	v_add_f32_dpp v228, v228, v228 quad_perm:[2,3,0,1] row_mask:0xf bank_mask:0xf
	v_add_f32_dpp v229, v229, v229 quad_perm:[2,3,0,1] row_mask:0xf bank_mask:0xf
	v_add_f32_dpp v230, v230, v230 quad_perm:[2,3,0,1] row_mask:0xf bank_mask:0xf
	v_add_f32_dpp v231, v231, v231 quad_perm:[2,3,0,1] row_mask:0xf bank_mask:0xf
	v_add_f32_dpp v232, v232, v232 quad_perm:[2,3,0,1] row_mask:0xf bank_mask:0xf
	v_add_f32_dpp v233, v233, v233 quad_perm:[2,3,0,1] row_mask:0xf bank_mask:0xf
	v_add_f32_dpp v234, v234, v234 quad_perm:[2,3,0,1] row_mask:0xf bank_mask:0xf
	v_add_f32_dpp v235, v235, v235 quad_perm:[2,3,0,1] row_mask:0xf bank_mask:0xf
	v_add_f32_dpp v236, v236, v236 quad_perm:[2,3,0,1] row_mask:0xf bank_mask:0xf
	v_add_f32_dpp v237, v237, v237 quad_perm:[2,3,0,1] row_mask:0xf bank_mask:0xf
	v_add_f32_dpp v238, v238, v238 quad_perm:[2,3,0,1] row_mask:0xf bank_mask:0xf
	v_add_f32_dpp v239, v239, v239 quad_perm:[2,3,0,1] row_mask:0xf bank_mask:0xf
	v_add_f32_dpp v240, v240, v240 quad_perm:[2,3,0,1] row_mask:0xf bank_mask:0xf
	v_add_f32_dpp v241, v241, v241 quad_perm:[2,3,0,1] row_mask:0xf bank_mask:0xf
	v_add_f32_dpp v242, v242, v242 quad_perm:[2,3,0,1] row_mask:0xf bank_mask:0xf
	v_add_f32_dpp v243, v243, v243 quad_perm:[2,3,0,1] row_mask:0xf bank_mask:0xf
	s_mov_b64 exec, s[2:3]
	ds_write_b128 v124, v[228:231]
	ds_write_b128 v124, v[232:235] offset:64
	ds_write_b128 v124, v[236:239] offset:128
	ds_write_b128 v124, v[240:243] offset:192
	s_mov_b64 exec, -1
	v_add_u32_e32 v124, 0x100, v124
	v_cvt_pk_bf16_f32 v244, v244, v245
	v_cvt_pk_bf16_f32 v245, v246, v247
	v_cvt_pk_bf16_f32 v246, v248, v249
	v_cvt_pk_bf16_f32 v247, v250, v251
	v_cvt_pk_bf16_f32 v248, v252, v253
	v_cvt_pk_bf16_f32 v249, v255, v98
	v_cvt_pk_bf16_f32 v250, v99, v116
	v_cvt_pk_bf16_f32 v251, v117, v118
	s_cmp_lg_u32 s22, s21
	s_cbranch_scc0 .Lc2s_last
	s_waitcnt vmcnt(1)
	v_mfma_f32_16x16x32_bf16 v[16:19], v[56:59], v[244:247], v[16:19]
	v_mfma_f32_16x16x32_bf16 v[20:23], v[64:67], v[244:247], v[20:23]
	v_mfma_f32_16x16x32_bf16 v[12:15], v[100:103], v[244:247], v[12:15]
	v_mfma_f32_16x16x32_bf16 v[8:11], v[108:111], v[244:247], v[8:11]
	v_mfma_f32_16x16x32_bf16 v[16:19], v[60:63], v[248:251], v[16:19]
	v_mfma_f32_16x16x32_bf16 v[20:23], v[68:71], v[248:251], v[20:23]
	v_mfma_f32_16x16x32_bf16 v[12:15], v[104:107], v[248:251], v[12:15]
	v_mfma_f32_16x16x32_bf16 v[8:11], v[112:115], v[248:251], v[8:11]
	global_load_dwordx4 v[56:59], v[122:123], off offset:-4096
	global_load_dwordx4 v[60:63], v[122:123], off offset:-3072
	global_load_dwordx4 v[64:67], v[122:123], off offset:-2048
	global_load_dwordx4 v[68:71], v[122:123], off offset:-1024
	global_load_dwordx4 v[100:103], v[122:123], off offset:0
	global_load_dwordx4 v[104:107], v[122:123], off offset:1024
	global_load_dwordx4 v[108:111], v[122:123], off offset:2048
	global_load_dwordx4 v[112:115], v[122:123], off offset:3072
	s_branch .Lc2s_loop

; __device__ __forceinline__ void nsa_wave(CArgs* Ap, int l, int b, int g, int tq0, const LAS float* lut, LAS float* imp, int lane) {
;     ...
;         float lt = st.l; lt += __shfl_xor(lt, 16); lt += __shfl_xor(lt, 32);
;         const float inv = 1.f / fmaxf(lt, 1e-30f), mfin = st.m;
;         for (int cb = 0; cb < ncb; ++cb) {
;             bf16x8 kf[4][2]; load_k(kf, KC + (size_t)cb * 4096, lane);
;             bf16x8 vf[4][2]; load_v(vf, VCT + (size_t)cb * 4096, lane);
.Lc2_orig:
	s_waitcnt lgkmcnt(0)
	v_add_f32_e32 v8, v24, v25
	v_max_f32_e32 v8, 0xda24260, v8
	v_div_scale_f32 v9, s[0:1], v8, v8, 1.0
	v_rcp_f32_e32 v10, v9
	v_div_scale_f32 v11, vcc, 1.0, v8, 1.0
	s_add_i32 s0, s20, s17
	v_fma_f32 v12, -v9, v10, 1.0
	v_fmac_f32_e32 v10, v12, v10
	v_mul_f32_e32 v12, v11, v10
	v_fma_f32 v13, -v9, v12, v11
	v_fmac_f32_e32 v12, v13, v10
	v_fma_f32 v9, -v9, v12, v11
	v_div_fmas_f32 v9, v9, v10, v12
	v_div_fixup_f32 v80, v9, v8, 1.0
	s_lshl_b32 s21, s21, 8
	s_ashr_i32 s1, s0, 31
	s_addk_i32 s21, 0x100
	s_lshl_b64 s[0:1], s[0:1], 16
	s_add_u32 s0, s15, s0
	s_addc_u32 s1, s16, s1
	s_mov_b32 s22, 0
	v_mov_b32_e32 v8, 0
	v_mov_b32_e32 v9, 0
	v_mov_b32_e32 v10, 0
	v_mov_b32_e32 v11, 0
	v_mov_b32_e32 v12, 0
	v_mov_b32_e32 v13, 0
	v_mov_b32_e32 v14, 0
	v_mov_b32_e32 v15, 0
	v_mov_b32_e32 v16, 0
	v_mov_b32_e32 v17, 0
	v_mov_b32_e32 v18, 0
	v_mov_b32_e32 v19, 0
	v_mov_b32_e32 v20, 0
	v_mov_b32_e32 v21, 0
	v_mov_b32_e32 v22, 0
	v_mov_b32_e32 v23, 0
	v_lshl_add_u64 v[126:127], s[0:1], 0, v[84:85]
	s_mov_b32 s23, 0x2a201000
	v_add_co_u32_e32 v120, vcc, s23, v126
	s_mov_b32 s23, 0x2a601000
	s_nop 0
	v_addc_co_u32_e32 v121, vcc, 0, v127, vcc
	v_add_co_u32_e32 v122, vcc, s23, v126
	v_add_u32_e32 v124, 0x10000, v203
	s_mov_b64 s[0:1], 0x2000
	v_addc_co_u32_e32 v123, vcc, 0, v127, vcc
	global_load_dwordx4 v[24:27], v[120:121], off offset:-4096
	global_load_dwordx4 v[28:31], v[120:121], off offset:-3072
	global_load_dwordx4 v[32:35], v[120:121], off offset:-2048
	global_load_dwordx4 v[36:39], v[120:121], off offset:-1024
	global_load_dwordx4 v[40:43], v[120:121], off offset:0
	global_load_dwordx4 v[44:47], v[120:121], off offset:1024
	global_load_dwordx4 v[48:51], v[120:121], off offset:2048
	global_load_dwordx4 v[52:55], v[120:121], off offset:3072
	global_load_dwordx4 v[56:59], v[122:123], off offset:-4096
	global_load_dwordx4 v[60:63], v[122:123], off offset:-3072
	global_load_dwordx4 v[64:67], v[122:123], off offset:-2048
	global_load_dwordx4 v[68:71], v[122:123], off offset:-1024
	global_load_dwordx4 v[100:103], v[122:123], off offset:0
	global_load_dwordx4 v[104:107], v[122:123], off offset:1024
	global_load_dwordx4 v[108:111], v[122:123], off offset:2048
	global_load_dwordx4 v[112:115], v[122:123], off offset:3072
	v_mul_f32_e32 v126, 0xbfb8aa3b, v76

; #define LAS __attribute__((address_space(3)))
; __global__ void __launch_bounds__(512, 2) hymba_fwd(Args A_unused) {
;     extern __shared__ __attribute__((aligned(16))) unsigned char lds_raw[];
;     LAS unsigned char* lds = (LAS unsigned char*)lds_raw;
	.amdhsa_kernel _Z9hymba_fwd4Args
		.amdhsa_group_segment_fixed_size 28672
		.amdhsa_private_segment_fixed_size 0
		.amdhsa_kernarg_size 480
		.amdhsa_user_sgpr_count 2
		.amdhsa_user_sgpr_dispatch_ptr 0
		.amdhsa_user_sgpr_queue_ptr 0
		.amdhsa_user_sgpr_kernarg_segment_ptr 1
		.amdhsa_user_sgpr_dispatch_id 0
		.amdhsa_user_sgpr_kernarg_preload_length 0
		.amdhsa_user_sgpr_kernarg_preload_offset 0
		.amdhsa_user_sgpr_private_segment_size 0
		.amdhsa_uses_dynamic_stack 0
		.amdhsa_enable_private_segment 0
		.amdhsa_system_sgpr_workgroup_id_x 1
		.amdhsa_system_sgpr_workgroup_id_y 0
		.amdhsa_system_sgpr_workgroup_id_z 0
		.amdhsa_system_sgpr_workgroup_info 0
		.amdhsa_system_vgpr_workitem_id 2
		.amdhsa_next_free_vgpr 256
		.amdhsa_next_free_sgpr 102
		.amdhsa_accum_offset 256
		.amdhsa_reserve_vcc 1
		.amdhsa_float_round_mode_32 0
		.amdhsa_float_round_mode_16_64 0
		.amdhsa_float_denorm_mode_32 3
		.amdhsa_float_denorm_mode_16_64 3
		.amdhsa_dx10_clamp 1
		.amdhsa_ieee_mode 1
		.amdhsa_fp16_overflow 0
		.amdhsa_tg_split 0
		.amdhsa_exception_fp_ieee_invalid_op 0
		.amdhsa_exception_fp_denorm_src 0
		.amdhsa_exception_fp_ieee_div_zero 0
		.amdhsa_exception_fp_ieee_overflow 0
		.amdhsa_exception_fp_ieee_underflow 0
		.amdhsa_exception_fp_ieee_inexact 0
		.amdhsa_exception_int_div_zero 0
	.end_amdhsa_kernel

; #define LAS __attribute__((address_space(3)))
; __global__ void __launch_bounds__(512, 2) hymba_fwd(Args A_unused) {
;     extern __shared__ __attribute__((aligned(16))) unsigned char lds_raw[];
;     LAS unsigned char* lds = (LAS unsigned char*)lds_raw;
amdhsa.kernels:
  - .agpr_count:     0
    .args:
      - .offset:         0
        .size:           224
        .value_kind:     by_value
      - .offset:         224
        .size:           4
        .value_kind:     hidden_block_count_x
      - .offset:         228
        .size:           4
        .value_kind:     hidden_block_count_y
      - .offset:         232
        .size:           4
        .value_kind:     hidden_block_count_z
      - .offset:         236
        .size:           2
        .value_kind:     hidden_group_size_x
      - .offset:         238
        .size:           2
        .value_kind:     hidden_group_size_y
      - .offset:         240
        .size:           2
        .value_kind:     hidden_group_size_z
      - .offset:         242
        .size:           2
        .value_kind:     hidden_remainder_x
      - .offset:         244
        .size:           2
        .value_kind:     hidden_remainder_y
      - .offset:         246
        .size:           2
        .value_kind:     hidden_remainder_z
      - .offset:         264
        .size:           8
        .value_kind:     hidden_global_offset_x
      - .offset:         272
        .size:           8
        .value_kind:     hidden_global_offset_y
      - .offset:         280
        .size:           8
        .value_kind:     hidden_global_offset_z
      - .offset:         288
        .size:           2
        .value_kind:     hidden_grid_dims
      - .offset:         312
        .size:           8
        .value_kind:     hidden_multigrid_sync_arg
      - .offset:         344
        .size:           4
        .value_kind:     hidden_dynamic_lds_size
    .group_segment_fixed_size: 28672
    .kernarg_segment_align: 8
    .kernarg_segment_size: 480
    .language:       OpenCL C
    .language_version:
      - 2
      - 0
    .max_flat_workgroup_size: 512
    .name:           _Z9hymba_fwd4Args
    .private_segment_fixed_size: 0
    .sgpr_count:     108
    .sgpr_spill_count: 43
    .symbol:         _Z9hymba_fwd4Args.kd
    .uniform_work_group_size: 1
    .uses_dynamic_stack: false
    .vgpr_count:     256
    .vgpr_spill_count: 0
    .wavefront_size: 64
